# attn1 tile loop unrolled x2 with hardcoded LDS slot offsets (no per-step address VALU / slot SALU)
# speedup vs baseline: 1.0553x; 1.0084x over previous
; #define LAS __attribute__((address_space(3)))
; #define ATT_GLOAD(t_) do { const size_t row_ = (size_t)(A.k_row0 + 64 * (t_)); \
;         kreg = *(const u32x4*)(A.K + (row_ + lkey) * A.k_stride + 8 * lpc); vreg = *(const u32x4*)(A.V + (row_ + lkey) * A.v_stride + 8 * lpc); \
;         if (DQ == 96 && tid < 256) k2reg = *(const u32x4*)(A.K2 + (row_ + l2key) * 32 + 8 * l2pc); } while (0)
; #define ATT_LSTORE(buf_) do { LAS unsigned char* kb_ = lds + (buf_) * KBUF; LAS unsigned char* vb_ = lds + 2 * KBUF + (buf_) * VBUF; \
;         *(LAS u32x4*)(kb_ + (lkey * KSTR + 8 * lpc) * 2) = kreg; *(LAS u32x4*)(vb_ + (lkey * VROW + 8 * lpc) * 2) = vreg; \
;         if (DQ == 96 && tid < 256) *(LAS u32x4*)(kb_ + (l2key * KSTR + 64 + 8 * l2pc) * 2) = k2reg; } while (0)
; template <int DQ, bool BIAS, bool TAIL>
; __device__ __forceinline__ void attn_item(const AttnItem& A, LAS unsigned char* lds, int wave_s_) {
;     ...
;     f32x16 o[2][2];
;     float zinit = 0.f; asm volatile("" : "+v"(zinit));
;     const f32x16 zero16v = {0.f, 0.f, 0.f, 0.f, 0.f, 0.f, 0.f, 0.f, 0.f, 0.f, 0.f, 0.f, 0.f, 0.f, 0.f, 0.f};
;     float mref[2] = {A.m0, A.m0};
; #pragma unroll
;     for (int qb = 0; qb < 2; ++qb)
; #pragma unroll
;         for (int i = 0; i < 16; ++i) { o[0][qb][i] = zinit; o[1][qb][i] = zinit; }
;     float lrun[2] = {hi == 0 ? A.l0 : 0.f, hi == 0 ? A.l0 : 0.f};
;     bool first = A.l0 == 0.f;
;     const int lkey = tid >> 3, lpc = tid & 7, l2key = tid >> 2, l2pc = tid & 3;
;     u32x4 kreg, k2reg, vreg;
;     ...
;     ATT_GLOAD(A.t_lo); ATT_LSTORE(0);
;     __syncthreads();
;     const int i16 = lane & 15, vlane_off = ((4 * hi + (i16 >> 2)) * VROW + 16 * ((lane >> 4) & 1) + 4 * (i16 & 3)) * 2;
;     const int koff = (r32 * KSTR + 8 * hi) * 2;
;     if (w < 4) __builtin_amdgcn_s_setprio(2);
;     int buf = 0;
;     for (int t = A.t_lo; t <= A.t_hi; ++t) {
;         const bool more = t < A.t_hi;
;         const bool act = t >= wlo && t <= whi;
;         const LAS unsigned char* kb = lds + buf * KBUF + koff; const LAS unsigned char* vb = lds + 2 * KBUF + buf * VBUF + vlane_off;
;         bf16x8 kf[NKK];
;         if (act) {
; #pragma unroll
;             for (int kk = 0; kk < NKK; ++kk) kf[kk] = *(const LAS bf16x8*)(kb + (16 * kk) * 2);
;         }
;         if (more) ATT_GLOAD(t + 1);
.LBB0_1472:
	v_lshlrev_b32_e32 v222, 2, v12
	v_lshrrev_b32_e32 v1, 2, v11
	v_and_b32_e32 v2, 16, v11
	v_lshlrev_b32_e32 v3, 2, v11
	v_and_b32_e32 v17, 63, v11
	v_and_or_b32 v1, v1, 3, v222
	v_and_or_b32 v2, v3, 12, v2
	s_movk_i32 s1, 0x48
	v_mad_u32_u24 v18, v1, s1, v2
	v_mul_u32_u24_e32 v19, 0xd0, v220
	v_mov_b64_e32 v[14:15], 0
	v_cmp_gt_u32_e64 s[4:5], 32, v17
	v_mov_b32_e32 v17, v197
	v_mov_b32_e32 v1, v0
	v_mov_b64_e32 v[2:3], 0
	v_mov_b64_e32 v[4:5], 0
	v_mov_b64_e32 v[6:7], 0
	v_mov_b64_e32 v[8:9], 0
	v_mov_b64_e32 v[10:11], 0
	v_mov_b64_e32 v[12:13], 0
	v_add3_u32 v228, 0, v196, v19
	v_lshl_add_u32 v227, v18, 1, 0
	v_lshl_add_u32 v214, v206, 11, v16
	s_nop 0
	v_mov_b32_e32 v211, v197
	v_mov_b32_e32 v196, v197
	v_mov_b64_e32 v[46:47], v[14:15]
	v_mov_b64_e32 v[30:31], v[14:15]
	v_mov_b64_e32 v[62:63], v[14:15]
	s_min_i32 s1, s20, s66
	v_lshl_add_u32 v218, v208, 6, v210
	s_add_i32 s89, s72, 64
	s_lshl_b32 s32, s89, 11
	s_add_u32 s90, s46, s32
	s_addc_u32 s91, s47, 0
	s_add_u32 s92, s48, s32
	s_addc_u32 s93, s49, 0
	s_lshl_b32 s32, s89, 6
	s_add_u32 s98, s40, s32
	s_addc_u32 s99, s41, 0
	s_mov_b32 s21, 0
	s_mov_b64 s[16:17], -1
	s_mov_b64 s[100:101], -1
	v_mov_b32_e32 v223, 0
	v_mov_b64_e32 v[44:45], v[12:13]
	v_mov_b64_e32 v[42:43], v[10:11]
	v_mov_b64_e32 v[40:41], v[8:9]
	v_mov_b64_e32 v[38:39], v[6:7]
	v_mov_b64_e32 v[36:37], v[4:5]
	v_mov_b64_e32 v[34:35], v[2:3]
	v_mov_b64_e32 v[32:33], v[0:1]
	v_mov_b64_e32 v[28:29], v[12:13]
	v_mov_b64_e32 v[26:27], v[10:11]
	v_mov_b64_e32 v[24:25], v[8:9]
	v_mov_b64_e32 v[22:23], v[6:7]
	v_mov_b64_e32 v[20:21], v[4:5]
	v_mov_b64_e32 v[18:19], v[2:3]
	v_mov_b64_e32 v[16:17], v[0:1]
	v_mov_b64_e32 v[60:61], v[12:13]
	v_mov_b64_e32 v[58:59], v[10:11]
	v_mov_b64_e32 v[56:57], v[8:9]
	v_mov_b64_e32 v[54:55], v[6:7]
	v_mov_b64_e32 v[52:53], v[4:5]
	v_mov_b64_e32 v[50:51], v[2:3]
	v_mov_b64_e32 v[48:49], v[0:1]
	v_mov_b32_e32 v211, 0
	s_mov_b32 s22, 0
	v_mov_b64_e32 v[212:213], v[196:197]
	v_mov_b32_e32 v196, v228
	v_add_u32_e32 v250, v210, v226
	s_branch .LBB0_1474

; #define LAS __attribute__((address_space(3)))
; template <int DQ, bool BIAS, bool TAIL>
; __device__ __forceinline__ void attn_item(const AttnItem& A, LAS unsigned char* lds, int wave_s_) {
;     ...
;     for (int t = A.t_lo; t <= A.t_hi; ++t) {
;         const bool more = t < A.t_hi;
;         const bool act = t >= wlo && t <= whi;
;         const LAS unsigned char* kb = lds + buf * KBUF + koff; const LAS unsigned char* vb = lds + 2 * KBUF + buf * VBUF + vlane_off;
;         bf16x8 kf[NKK];
;         if (act) {
; #pragma unroll
;             for (int kk = 0; kk < NKK; ++kk) kf[kk] = *(const LAS bf16x8*)(kb + (16 * kk) * 2);
;         }
.Lp9_topB:
	s_cmp_le_i32 s22, s1
	s_cselect_b64 s[8:9], -1, 0
	s_cmp_gt_i32 s22, s1
	s_cbranch_scc1 .Lp9_ldB
	ds_read_b128 v[176:179], v228 offset:13312
	ds_read_b128 v[172:175], v228 offset:13344
	ds_read_b128 v[168:171], v228 offset:13376
	ds_read_b128 v[164:167], v228 offset:13408
	ds_read_b128 v[160:163], v228 offset:13440
	ds_read_b128 v[156:159], v228 offset:13472

; template <int DQ, bool BIAS, bool TAIL>
; __device__ __forceinline__ void attn_item(const AttnItem& A, LAS unsigned char* lds, int wave_s_) {
;     ...
;                 s[0] = MFMA32(kf[0], qf[0][0], zero16v); s[1] = MFMA32(kf[0], qf[1][0], zero16v);
; #pragma unroll
;                 for (int kk = 1; kk < NKK; ++kk) { s[0] = MFMA32(kf[kk], qf[0][kk], s[0]); s[1] = MFMA32(kf[kk], qf[1][kk], s[1]); }
;                 s16x4 vlo[2][2], vhi[2][2];
; #pragma unroll
;                 for (int st = 0; st < 2; ++st)
; #pragma unroll
;                     for (int d = 0; d < 2; ++d) { const LAS unsigned char* vp = vb + ((32 * kbk + 16 * st) * VROW + 32 * d) * 2; vlo[st][d] = vtr(vp); vhi[st][d] = vtr(vp + 8 * VROW * 2); }
;                 __builtin_amdgcn_sched_barrier(0);
;                 float mx[2];
; #pragma unroll
;                 for (int qb = 0; qb < 2; ++qb) {
;                     if (BIAS || TAIL) {
;                         const int qk = A.q_kidx0 + 64 * w + 32 * qb + r32;
; #pragma unroll
;                         for (int i = 0; i < 16; ++i) { const int kidx = 64 * t + 32 * kbk + crow(i, hi);
;                             float v = s[qb][i]; if (BIAS) v += lut[kidx - qk + LUT0]; if (TAIL && kidx >= A.nkeys) v = -1.0e30f; s[qb][i] = v; }
;                     }
;                     const float t0 = max3f(s[qb][0], s[qb][1], s[qb][2]), t1 = max3f(s[qb][3], s[qb][4], s[qb][5]), t2 = max3f(s[qb][6], s[qb][7], s[qb][8]),
;                                 t3 = max3f(s[qb][9], s[qb][10], s[qb][11]), t4 = max3f(s[qb][12], s[qb][13], s[qb][14]);
;                     const float m = max3f(max3f(t0, t1, t2), max3f(t3, t4, s[qb][15]), t0);
;                     mx[qb] = swapmax(m, hi) - mref[qb];
;                 }
;                 const bool need0 = first || mx[0] > RESCALE_THR, need1 = first || mx[1] > RESCALE_THR;
;                 if (__builtin_amdgcn_ballot_w64(need0 || need1) != 0ull) {
; #pragma unroll
;                     for (int qb = 0; qb < 2; ++qb) {
;                         const float delta = (qb == 0 ? need0 : need1) ? mx[qb] : 0.f, alpha = __builtin_amdgcn_exp2f(-delta);
; #pragma unroll
;                         for (int i = 0; i < 16; ++i) { o[0][qb][i] *= alpha; o[1][qb][i] *= alpha; }
;                         lrun[qb] *= alpha; mref[qb] += delta;
;                     }
;                     first = false;
;                 }
.Lp9_ldB2:
	s_or_b64 exec, exec, s[10:11]
	s_andn2_b64 vcc, exec, s[8:9]
	s_cbranch_vccnz .Lp9_botB
	v_mfma_f32_32x32x16_bf16 v[80:95], v[230:233], v[238:241], 0
	s_waitcnt lgkmcnt(5)
	v_mfma_f32_32x32x16_bf16 v[80:95], v[176:179], v[96:99], v[80:95]
	ds_read_b64_tr_b16 v[192:193], v227 offset:35840
	ds_read_b64_tr_b16 v[194:195], v227 offset:36992
	ds_read_b64_tr_b16 v[188:189], v227 offset:35904
	ds_read_b64_tr_b16 v[190:191], v227 offset:37056
	ds_read_b64_tr_b16 v[184:185], v227 offset:38144
	ds_read_b64_tr_b16 v[186:187], v227 offset:39296
	ds_read_b64_tr_b16 v[180:181], v227 offset:38208
	ds_read_b64_tr_b16 v[182:183], v227 offset:39360
	s_waitcnt lgkmcnt(12)
	v_mfma_f32_32x32x16_bf16 v[80:95], v[172:175], v[100:103], v[80:95]
	s_waitcnt lgkmcnt(11)
	v_mfma_f32_32x32x16_bf16 v[80:95], v[168:171], v[104:107], v[80:95]
	s_waitcnt lgkmcnt(10)
	v_mfma_f32_32x32x16_bf16 v[80:95], v[164:167], v[108:111], v[80:95]
	s_waitcnt lgkmcnt(9)
	v_mfma_f32_32x32x16_bf16 v[80:95], v[160:163], v[112:115], v[80:95]
	s_waitcnt lgkmcnt(8)
	v_mfma_f32_32x32x16_bf16 v[80:95], v[156:159], v[116:119], v[80:95]
	v_mfma_f32_32x32x16_bf16 v[64:79], v[230:233], v[246:249], 0
	v_mfma_f32_32x32x16_bf16 v[64:79], v[176:179], v[120:123], v[64:79]
	ds_read_b128 v[176:179], v228 offset:19968
	v_mfma_f32_32x32x16_bf16 v[64:79], v[172:175], v[124:127], v[64:79]
	ds_read_b128 v[172:175], v228 offset:20000
	s_nop 7
	v_exp_f32_e32 v80, v80
	v_exp_f32_e32 v81, v81
	v_exp_f32_e32 v82, v82
	v_exp_f32_e32 v83, v83
	v_exp_f32_e32 v84, v84
	v_exp_f32_e32 v85, v85
	v_mfma_f32_32x32x16_bf16 v[64:79], v[168:171], v[128:131], v[64:79]
	ds_read_b128 v[168:171], v228 offset:20032
	v_exp_f32_e32 v86, v86
	v_exp_f32_e32 v87, v87
	v_add_f32_e32 v198, v80, v84
	v_add_f32_e32 v199, v81, v85
	v_add_f32_e32 v204, v82, v86
	v_add_f32_e32 v205, v83, v87
	v_exp_f32_e32 v88, v88
	v_exp_f32_e32 v89, v89
	v_mfma_f32_32x32x16_bf16 v[64:79], v[164:167], v[132:135], v[64:79]
	ds_read_b128 v[164:167], v228 offset:20064
	v_exp_f32_e32 v90, v90
	v_exp_f32_e32 v91, v91
	v_add_f32_e32 v198, v198, v88
	v_add_f32_e32 v199, v199, v89
	v_add_f32_e32 v204, v204, v90
	v_add_f32_e32 v205, v205, v91
	v_exp_f32_e32 v92, v92
	v_exp_f32_e32 v93, v93
	v_mfma_f32_32x32x16_bf16 v[64:79], v[160:163], v[140:143], v[64:79]
	ds_read_b128 v[160:163], v228 offset:20096
	v_exp_f32_e32 v94, v94
	v_exp_f32_e32 v95, v95
	v_add_f32_e32 v198, v198, v92
	v_add_f32_e32 v199, v199, v93
	v_add_f32_e32 v204, v204, v94
	v_add_f32_e32 v205, v205, v95
	v_mfma_f32_32x32x16_bf16 v[64:79], v[156:159], v[136:139], v[64:79]
	ds_read_b128 v[156:159], v228 offset:20128
	v_add_f32_e32 v198, v198, v199
	v_add_f32_e32 v204, v204, v205
	v_add_f32_e32 v198, v198, v204
	v_cmp_lt_f32_e32 vcc, 0x44800000, v198
	s_or_b32 s8, vcc_lo, vcc_hi
	s_mov_b32 s9, s8
	s_cbranch_scc1 .Lp7b_rare_00

; template <int DQ, bool BIAS, bool TAIL>
; __device__ __forceinline__ void attn_item(const AttnItem& A, LAS unsigned char* lds, int wave_s_) {
;     ...
;                 s[0] = MFMA32(kf[0], qf[0][0], zero16v); s[1] = MFMA32(kf[0], qf[1][0], zero16v);
; #pragma unroll
;                 for (int kk = 1; kk < NKK; ++kk) { s[0] = MFMA32(kf[kk], qf[0][kk], s[0]); s[1] = MFMA32(kf[kk], qf[1][kk], s[1]); }
;                 s16x4 vlo[2][2], vhi[2][2];
; #pragma unroll
;                 for (int st = 0; st < 2; ++st)
; #pragma unroll
;                     for (int d = 0; d < 2; ++d) { const LAS unsigned char* vp = vb + ((32 * kbk + 16 * st) * VROW + 32 * d) * 2; vlo[st][d] = vtr(vp); vhi[st][d] = vtr(vp + 8 * VROW * 2); }
;                 __builtin_amdgcn_sched_barrier(0);
;                 float mx[2];
; #pragma unroll
;                 for (int qb = 0; qb < 2; ++qb) {
;                     if (BIAS || TAIL) {
;                         const int qk = A.q_kidx0 + 64 * w + 32 * qb + r32;
; #pragma unroll
;                         for (int i = 0; i < 16; ++i) { const int kidx = 64 * t + 32 * kbk + crow(i, hi);
;                             float v = s[qb][i]; if (BIAS) v += lut[kidx - qk + LUT0]; if (TAIL && kidx >= A.nkeys) v = -1.0e30f; s[qb][i] = v; }
;                     }
;                     const float t0 = max3f(s[qb][0], s[qb][1], s[qb][2]), t1 = max3f(s[qb][3], s[qb][4], s[qb][5]), t2 = max3f(s[qb][6], s[qb][7], s[qb][8]),
;                                 t3 = max3f(s[qb][9], s[qb][10], s[qb][11]), t4 = max3f(s[qb][12], s[qb][13], s[qb][14]);
;                     const float m = max3f(max3f(t0, t1, t2), max3f(t3, t4, s[qb][15]), t0);
;                     mx[qb] = swapmax(m, hi) - mref[qb];
;                 }
;                 const bool need0 = first || mx[0] > RESCALE_THR, need1 = first || mx[1] > RESCALE_THR;
;                 if (__builtin_amdgcn_ballot_w64(need0 || need1) != 0ull) {
; #pragma unroll
;                     for (int qb = 0; qb < 2; ++qb) {
;                         const float delta = (qb == 0 ? need0 : need1) ? mx[qb] : 0.f, alpha = __builtin_amdgcn_exp2f(-delta);
; #pragma unroll
;                         for (int i = 0; i < 16; ++i) { o[0][qb][i] *= alpha; o[1][qb][i] *= alpha; }
;                         lrun[qb] *= alpha; mref[qb] += delta;
;                     }
;                     first = false;
;                 }
.Lp7b_back_01:
	v_cvt_pk_bf16_f32 v64, v64, v65
	v_cvt_pk_bf16_f32 v65, v66, v67
	v_cvt_pk_bf16_f32 v66, v68, v69
	v_cvt_pk_bf16_f32 v67, v70, v71
	v_add_f32_e32 v213, v213, v198
	v_cvt_pk_bf16_f32 v68, v72, v73
	v_cvt_pk_bf16_f32 v69, v74, v75
	v_cvt_pk_bf16_f32 v70, v76, v77
	v_cvt_pk_bf16_f32 v71, v78, v79
	v_exp_f32_e32 v80, v80
	v_exp_f32_e32 v81, v81
	v_mfma_f32_32x32x16_bf16 v[16:31], v[192:195], v[64:67], v[16:31]
	v_exp_f32_e32 v82, v82
	v_exp_f32_e32 v83, v83
	v_mfma_f32_32x32x16_bf16 v[0:15], v[188:191], v[64:67], v[0:15]
	v_exp_f32_e32 v84, v84
	v_exp_f32_e32 v85, v85
	v_mfma_f32_32x32x16_bf16 v[16:31], v[184:187], v[68:71], v[16:31]
	v_exp_f32_e32 v86, v86
	v_exp_f32_e32 v87, v87
	v_mfma_f32_32x32x16_bf16 v[0:15], v[180:183], v[68:71], v[0:15]
	ds_read_b64_tr_b16 v[192:193], v227 offset:40448
	ds_read_b64_tr_b16 v[194:195], v227 offset:41600
	ds_read_b64_tr_b16 v[188:189], v227 offset:40512
	ds_read_b64_tr_b16 v[190:191], v227 offset:41664
	ds_read_b64_tr_b16 v[184:185], v227 offset:42752
	ds_read_b64_tr_b16 v[186:187], v227 offset:43904
	ds_read_b64_tr_b16 v[180:181], v227 offset:42816
	ds_read_b64_tr_b16 v[182:183], v227 offset:43968
	v_add_f32_e32 v198, v80, v84
	v_add_f32_e32 v199, v81, v85
	v_mfma_f32_32x32x16_bf16 v[64:79], v[230:233], v[246:249], 0
	v_add_f32_e32 v204, v82, v86
	v_add_f32_e32 v205, v83, v87
	v_exp_f32_e32 v88, v88
	v_mfma_f32_32x32x16_bf16 v[64:79], v[176:179], v[120:123], v[64:79]
	v_exp_f32_e32 v89, v89
	v_exp_f32_e32 v90, v90
	v_exp_f32_e32 v91, v91
	v_mfma_f32_32x32x16_bf16 v[64:79], v[172:175], v[124:127], v[64:79]
	v_add_f32_e32 v198, v198, v88
	v_add_f32_e32 v199, v199, v89
	v_add_f32_e32 v204, v204, v90
	v_mfma_f32_32x32x16_bf16 v[64:79], v[168:171], v[128:131], v[64:79]
	v_add_f32_e32 v205, v205, v91
	v_exp_f32_e32 v92, v92
	v_exp_f32_e32 v93, v93
	v_mfma_f32_32x32x16_bf16 v[64:79], v[164:167], v[132:135], v[64:79]
	v_exp_f32_e32 v94, v94
	v_exp_f32_e32 v95, v95
	v_add_f32_e32 v198, v198, v92
	v_mfma_f32_32x32x16_bf16 v[64:79], v[160:163], v[140:143], v[64:79]
	v_add_f32_e32 v199, v199, v93
	v_add_f32_e32 v204, v204, v94
	v_add_f32_e32 v205, v205, v95
	v_mfma_f32_32x32x16_bf16 v[64:79], v[156:159], v[136:139], v[64:79]
	v_add_f32_e32 v198, v198, v199
	v_add_f32_e32 v204, v204, v205
	v_add_f32_e32 v198, v198, v204
	v_cmp_lt_f32_e32 vcc, 0x44800000, v198
	s_or_b32 s8, vcc_lo, vcc_hi
	s_mov_b32 s9, s8
	s_cbranch_scc1 .Lp7b_rare_10

; #define ATT_LSTORE(buf_) do { LAS unsigned char* kb_ = lds + (buf_) * KBUF; LAS unsigned char* vb_ = lds + 2 * KBUF + (buf_) * VBUF; \
;         *(LAS u32x4*)(kb_ + (lkey * KSTR + 8 * lpc) * 2) = kreg; *(LAS u32x4*)(vb_ + (lkey * VROW + 8 * lpc) * 2) = vreg; \
;         if (DQ == 96 && tid < 256) *(LAS u32x4*)(kb_ + (l2key * KSTR + 64 + 8 * l2pc) * 2) = k2reg; } while (0)
; template <int DQ, bool BIAS, bool TAIL>
; __device__ __forceinline__ void attn_item(const AttnItem& A, LAS unsigned char* lds, int wave_s_) {
;     ...
;         if (more) ATT_LSTORE(buf ^ 1);
;         __syncthreads();
;         buf ^= 1;
.Lp9_botB:
	s_movk_i32 s11, 0x0
	s_movk_i32 s19, 0x0
	s_movk_i32 s10, 0x0
	s_mov_b32 s21, 0
	s_waitcnt vmcnt(1)
	ds_write_b128 v224, v[152:155]
	s_waitcnt vmcnt(0)
	ds_write_b128 v225, v[148:151] offset:26624
	s_and_saveexec_b64 s[8:9], s[6:7]
	s_cbranch_execz .Lp9_latB
	ds_write_b128 v250, v[144:147] offset:128

; #define LAS __attribute__((address_space(3)))
; template <int DQ, bool BIAS, bool TAIL>
; __device__ __forceinline__ void attn_item(const AttnItem& A, LAS unsigned char* lds, int wave_s_) {
;     ...
;     for (int t = A.t_lo; t <= A.t_hi; ++t) {
;         const bool more = t < A.t_hi;
;         const bool act = t >= wlo && t <= whi;
;         const LAS unsigned char* kb = lds + buf * KBUF + koff; const LAS unsigned char* vb = lds + 2 * KBUF + buf * VBUF + vlane_off;
;         bf16x8 kf[NKK];
;         if (act) {
; #pragma unroll
;             for (int kk = 0; kk < NKK; ++kk) kf[kk] = *(const LAS bf16x8*)(kb + (16 * kk) * 2);
;         }
.LBB0_1474:
	s_cmp_le_i32 s22, s1
	s_cselect_b64 s[8:9], -1, 0
	s_cmp_gt_i32 s22, s1
	s_cbranch_scc1 .LBB0_1476
	ds_read_b128 v[176:179], v228
	ds_read_b128 v[172:175], v228 offset:32
	ds_read_b128 v[168:171], v228 offset:64
	ds_read_b128 v[164:167], v228 offset:96
	ds_read_b128 v[160:163], v228 offset:128
	ds_read_b128 v[156:159], v228 offset:160

; template <int DQ, bool BIAS, bool TAIL>
; __device__ __forceinline__ void attn_item(const AttnItem& A, LAS unsigned char* lds, int wave_s_) {
;     ...
;                 s[0] = MFMA32(kf[0], qf[0][0], zero16v); s[1] = MFMA32(kf[0], qf[1][0], zero16v);
; #pragma unroll
;                 for (int kk = 1; kk < NKK; ++kk) { s[0] = MFMA32(kf[kk], qf[0][kk], s[0]); s[1] = MFMA32(kf[kk], qf[1][kk], s[1]); }
;                 s16x4 vlo[2][2], vhi[2][2];
; #pragma unroll
;                 for (int st = 0; st < 2; ++st)
; #pragma unroll
;                     for (int d = 0; d < 2; ++d) { const LAS unsigned char* vp = vb + ((32 * kbk + 16 * st) * VROW + 32 * d) * 2; vlo[st][d] = vtr(vp); vhi[st][d] = vtr(vp + 8 * VROW * 2); }
;                 __builtin_amdgcn_sched_barrier(0);
;                 float mx[2];
; #pragma unroll
;                 for (int qb = 0; qb < 2; ++qb) {
;                     if (BIAS || TAIL) {
;                         const int qk = A.q_kidx0 + 64 * w + 32 * qb + r32;
; #pragma unroll
;                         for (int i = 0; i < 16; ++i) { const int kidx = 64 * t + 32 * kbk + crow(i, hi);
;                             float v = s[qb][i]; if (BIAS) v += lut[kidx - qk + LUT0]; if (TAIL && kidx >= A.nkeys) v = -1.0e30f; s[qb][i] = v; }
;                     }
;                     const float t0 = max3f(s[qb][0], s[qb][1], s[qb][2]), t1 = max3f(s[qb][3], s[qb][4], s[qb][5]), t2 = max3f(s[qb][6], s[qb][7], s[qb][8]),
;                                 t3 = max3f(s[qb][9], s[qb][10], s[qb][11]), t4 = max3f(s[qb][12], s[qb][13], s[qb][14]);
;                     const float m = max3f(max3f(t0, t1, t2), max3f(t3, t4, s[qb][15]), t0);
;                     mx[qb] = swapmax(m, hi) - mref[qb];
;                 }
;                 const bool need0 = first || mx[0] > RESCALE_THR, need1 = first || mx[1] > RESCALE_THR;
;                 if (__builtin_amdgcn_ballot_w64(need0 || need1) != 0ull) {
; #pragma unroll
;                     for (int qb = 0; qb < 2; ++qb) {
;                         const float delta = (qb == 0 ? need0 : need1) ? mx[qb] : 0.f, alpha = __builtin_amdgcn_exp2f(-delta);
; #pragma unroll
;                         for (int i = 0; i < 16; ++i) { o[0][qb][i] *= alpha; o[1][qb][i] *= alpha; }
;                         lrun[qb] *= alpha; mref[qb] += delta;
;                     }
;                     first = false;
;                 }
.Lp9_bodyA:
	v_mfma_f32_32x32x16_bf16 v[80:95], v[230:233], v[238:241], 0
	s_waitcnt lgkmcnt(5)
	v_mfma_f32_32x32x16_bf16 v[80:95], v[176:179], v[96:99], v[80:95]
	ds_read_b64_tr_b16 v[192:193], v227 offset:26624
	ds_read_b64_tr_b16 v[194:195], v227 offset:27776
	ds_read_b64_tr_b16 v[188:189], v227 offset:26688
	ds_read_b64_tr_b16 v[190:191], v227 offset:27840
	ds_read_b64_tr_b16 v[184:185], v227 offset:28928
	ds_read_b64_tr_b16 v[186:187], v227 offset:30080
	ds_read_b64_tr_b16 v[180:181], v227 offset:28992
	ds_read_b64_tr_b16 v[182:183], v227 offset:30144
	s_waitcnt lgkmcnt(12)
	v_mfma_f32_32x32x16_bf16 v[80:95], v[172:175], v[100:103], v[80:95]
	s_waitcnt lgkmcnt(11)
	v_mfma_f32_32x32x16_bf16 v[80:95], v[168:171], v[104:107], v[80:95]
	s_waitcnt lgkmcnt(10)
	v_mfma_f32_32x32x16_bf16 v[80:95], v[164:167], v[108:111], v[80:95]
	s_waitcnt lgkmcnt(9)
	v_mfma_f32_32x32x16_bf16 v[80:95], v[160:163], v[112:115], v[80:95]
	s_waitcnt lgkmcnt(8)
	v_mfma_f32_32x32x16_bf16 v[80:95], v[156:159], v[116:119], v[80:95]
	v_mfma_f32_32x32x16_bf16 v[64:79], v[230:233], v[246:249], 0
	v_mfma_f32_32x32x16_bf16 v[64:79], v[176:179], v[120:123], v[64:79]
	ds_read_b128 v[176:179], v228 offset:6656
	v_mfma_f32_32x32x16_bf16 v[64:79], v[172:175], v[124:127], v[64:79]
	ds_read_b128 v[172:175], v228 offset:6688
	s_nop 7
	v_exp_f32_e32 v80, v80
	v_exp_f32_e32 v81, v81
	v_exp_f32_e32 v82, v82
	v_exp_f32_e32 v83, v83
	v_exp_f32_e32 v84, v84
	v_exp_f32_e32 v85, v85
	v_mfma_f32_32x32x16_bf16 v[64:79], v[168:171], v[128:131], v[64:79]
	ds_read_b128 v[168:171], v228 offset:6720
	v_exp_f32_e32 v86, v86
	v_exp_f32_e32 v87, v87
	v_add_f32_e32 v198, v80, v84
	v_add_f32_e32 v199, v81, v85
	v_add_f32_e32 v204, v82, v86
	v_add_f32_e32 v205, v83, v87
	v_exp_f32_e32 v88, v88
	v_exp_f32_e32 v89, v89
	v_mfma_f32_32x32x16_bf16 v[64:79], v[164:167], v[132:135], v[64:79]
	ds_read_b128 v[164:167], v228 offset:6752
	v_exp_f32_e32 v90, v90
	v_exp_f32_e32 v91, v91
	v_add_f32_e32 v198, v198, v88
	v_add_f32_e32 v199, v199, v89
	v_add_f32_e32 v204, v204, v90
	v_add_f32_e32 v205, v205, v91
	v_exp_f32_e32 v92, v92
	v_exp_f32_e32 v93, v93
	v_mfma_f32_32x32x16_bf16 v[64:79], v[160:163], v[140:143], v[64:79]
	ds_read_b128 v[160:163], v228 offset:6784
	v_exp_f32_e32 v94, v94
	v_exp_f32_e32 v95, v95
	v_add_f32_e32 v198, v198, v92
	v_add_f32_e32 v199, v199, v93
	v_add_f32_e32 v204, v204, v94
	v_add_f32_e32 v205, v205, v95
	v_mfma_f32_32x32x16_bf16 v[64:79], v[156:159], v[136:139], v[64:79]
	ds_read_b128 v[156:159], v228 offset:6816
	v_add_f32_e32 v198, v198, v199
	v_add_f32_e32 v204, v204, v205
	v_add_f32_e32 v198, v198, v204
	v_cmp_lt_f32_e32 vcc, 0x44800000, v198
	s_or_b32 s8, vcc_lo, vcc_hi
	s_mov_b32 s9, s8
	s_cbranch_scc1 .Lp7a_rare_00

; template <int DQ, bool BIAS, bool TAIL>
; __device__ __forceinline__ void attn_item(const AttnItem& A, LAS unsigned char* lds, int wave_s_) {
;     ...
;                 s[0] = MFMA32(kf[0], qf[0][0], zero16v); s[1] = MFMA32(kf[0], qf[1][0], zero16v);
; #pragma unroll
;                 for (int kk = 1; kk < NKK; ++kk) { s[0] = MFMA32(kf[kk], qf[0][kk], s[0]); s[1] = MFMA32(kf[kk], qf[1][kk], s[1]); }
;                 s16x4 vlo[2][2], vhi[2][2];
; #pragma unroll
;                 for (int st = 0; st < 2; ++st)
; #pragma unroll
;                     for (int d = 0; d < 2; ++d) { const LAS unsigned char* vp = vb + ((32 * kbk + 16 * st) * VROW + 32 * d) * 2; vlo[st][d] = vtr(vp); vhi[st][d] = vtr(vp + 8 * VROW * 2); }
;                 __builtin_amdgcn_sched_barrier(0);
;                 float mx[2];
; #pragma unroll
;                 for (int qb = 0; qb < 2; ++qb) {
;                     if (BIAS || TAIL) {
;                         const int qk = A.q_kidx0 + 64 * w + 32 * qb + r32;
; #pragma unroll
;                         for (int i = 0; i < 16; ++i) { const int kidx = 64 * t + 32 * kbk + crow(i, hi);
;                             float v = s[qb][i]; if (BIAS) v += lut[kidx - qk + LUT0]; if (TAIL && kidx >= A.nkeys) v = -1.0e30f; s[qb][i] = v; }
;                     }
;                     const float t0 = max3f(s[qb][0], s[qb][1], s[qb][2]), t1 = max3f(s[qb][3], s[qb][4], s[qb][5]), t2 = max3f(s[qb][6], s[qb][7], s[qb][8]),
;                                 t3 = max3f(s[qb][9], s[qb][10], s[qb][11]), t4 = max3f(s[qb][12], s[qb][13], s[qb][14]);
;                     const float m = max3f(max3f(t0, t1, t2), max3f(t3, t4, s[qb][15]), t0);
;                     mx[qb] = swapmax(m, hi) - mref[qb];
;                 }
;                 const bool need0 = first || mx[0] > RESCALE_THR, need1 = first || mx[1] > RESCALE_THR;
;                 if (__builtin_amdgcn_ballot_w64(need0 || need1) != 0ull) {
; #pragma unroll
;                     for (int qb = 0; qb < 2; ++qb) {
;                         const float delta = (qb == 0 ? need0 : need1) ? mx[qb] : 0.f, alpha = __builtin_amdgcn_exp2f(-delta);
; #pragma unroll
;                         for (int i = 0; i < 16; ++i) { o[0][qb][i] *= alpha; o[1][qb][i] *= alpha; }
;                         lrun[qb] *= alpha; mref[qb] += delta;
;                     }
;                     first = false;
;                 }
.Lp7a_back_01:
	v_cvt_pk_bf16_f32 v64, v64, v65
	v_cvt_pk_bf16_f32 v65, v66, v67
	v_cvt_pk_bf16_f32 v66, v68, v69
	v_cvt_pk_bf16_f32 v67, v70, v71
	v_add_f32_e32 v213, v213, v198
	v_cvt_pk_bf16_f32 v68, v72, v73
	v_cvt_pk_bf16_f32 v69, v74, v75
	v_cvt_pk_bf16_f32 v70, v76, v77
	v_cvt_pk_bf16_f32 v71, v78, v79
	v_exp_f32_e32 v80, v80
	v_exp_f32_e32 v81, v81
	v_mfma_f32_32x32x16_bf16 v[16:31], v[192:195], v[64:67], v[16:31]
	v_exp_f32_e32 v82, v82
	v_exp_f32_e32 v83, v83
	v_mfma_f32_32x32x16_bf16 v[0:15], v[188:191], v[64:67], v[0:15]
	v_exp_f32_e32 v84, v84
	v_exp_f32_e32 v85, v85
	v_mfma_f32_32x32x16_bf16 v[16:31], v[184:187], v[68:71], v[16:31]
	v_exp_f32_e32 v86, v86
	v_exp_f32_e32 v87, v87
	v_mfma_f32_32x32x16_bf16 v[0:15], v[180:183], v[68:71], v[0:15]
	ds_read_b64_tr_b16 v[192:193], v227 offset:31232
	ds_read_b64_tr_b16 v[194:195], v227 offset:32384
	ds_read_b64_tr_b16 v[188:189], v227 offset:31296
	ds_read_b64_tr_b16 v[190:191], v227 offset:32448
	ds_read_b64_tr_b16 v[184:185], v227 offset:33536
	ds_read_b64_tr_b16 v[186:187], v227 offset:34688
	ds_read_b64_tr_b16 v[180:181], v227 offset:33600
	ds_read_b64_tr_b16 v[182:183], v227 offset:34752
	v_add_f32_e32 v198, v80, v84
	v_add_f32_e32 v199, v81, v85
	v_mfma_f32_32x32x16_bf16 v[64:79], v[230:233], v[246:249], 0
	v_add_f32_e32 v204, v82, v86
	v_add_f32_e32 v205, v83, v87
	v_exp_f32_e32 v88, v88
	v_mfma_f32_32x32x16_bf16 v[64:79], v[176:179], v[120:123], v[64:79]
	v_exp_f32_e32 v89, v89
	v_exp_f32_e32 v90, v90
	v_exp_f32_e32 v91, v91
	v_mfma_f32_32x32x16_bf16 v[64:79], v[172:175], v[124:127], v[64:79]
	v_add_f32_e32 v198, v198, v88
	v_add_f32_e32 v199, v199, v89
	v_add_f32_e32 v204, v204, v90
	v_mfma_f32_32x32x16_bf16 v[64:79], v[168:171], v[128:131], v[64:79]
	v_add_f32_e32 v205, v205, v91
	v_exp_f32_e32 v92, v92
	v_exp_f32_e32 v93, v93
	v_mfma_f32_32x32x16_bf16 v[64:79], v[164:167], v[132:135], v[64:79]
	v_exp_f32_e32 v94, v94
	v_exp_f32_e32 v95, v95
	v_add_f32_e32 v198, v198, v92
	v_mfma_f32_32x32x16_bf16 v[64:79], v[160:163], v[140:143], v[64:79]
	v_add_f32_e32 v199, v199, v93
	v_add_f32_e32 v204, v204, v94
	v_add_f32_e32 v205, v205, v95
	v_mfma_f32_32x32x16_bf16 v[64:79], v[156:159], v[136:139], v[64:79]
	v_add_f32_e32 v198, v198, v199
	v_add_f32_e32 v204, v204, v205
	v_add_f32_e32 v198, v198, v204
	v_cmp_lt_f32_e32 vcc, 0x44800000, v198
	s_or_b32 s8, vcc_lo, vcc_hi
	s_mov_b32 s9, s8
	s_cbranch_scc1 .Lp7a_rare_10

; #define ATT_LSTORE(buf_) do { LAS unsigned char* kb_ = lds + (buf_) * KBUF; LAS unsigned char* vb_ = lds + 2 * KBUF + (buf_) * VBUF; \
;         *(LAS u32x4*)(kb_ + (lkey * KSTR + 8 * lpc) * 2) = kreg; *(LAS u32x4*)(vb_ + (lkey * VROW + 8 * lpc) * 2) = vreg; \
;         if (DQ == 96 && tid < 256) *(LAS u32x4*)(kb_ + (l2key * KSTR + 64 + 8 * l2pc) * 2) = k2reg; } while (0)
; template <int DQ, bool BIAS, bool TAIL>
; __device__ __forceinline__ void attn_item(const AttnItem& A, LAS unsigned char* lds, int wave_s_) {
;     ...
;                 const bool need0 = first || mx[0] > RESCALE_THR, need1 = first || mx[1] > RESCALE_THR;
;                 if (__builtin_amdgcn_ballot_w64(need0 || need1) != 0ull) {
; #pragma unroll
;                     for (int qb = 0; qb < 2; ++qb) {
;                         const float delta = (qb == 0 ? need0 : need1) ? mx[qb] : 0.f, alpha = __builtin_amdgcn_exp2f(-delta);
; #pragma unroll
;                         for (int i = 0; i < 16; ++i) { o[0][qb][i] *= alpha; o[1][qb][i] *= alpha; }
;                         lrun[qb] *= alpha; mref[qb] += delta;
;                     }
;                     first = false;
;                 }
;     ...
;         if (more) ATT_LSTORE(buf ^ 1);
;         __syncthreads();
;         buf ^= 1;
.Lp7_fix:
	s_nop 15
	s_nop 7
	v_mov_b32_e32 v198, 0x3f80
	v_mov_b32_e32 v230, 0
	s_mov_b32 exec_hi, 0
	v_mov_b32_e32 v230, v198
	s_mov_b32 exec_hi, -1
	v_mov_b32_e32 v231, 0
	v_mov_b32_e32 v232, 0
	v_mov_b32_e32 v233, 0
	v_xor_b32_e32 v234, 0x80000000, v211
	v_cvt_pk_bf16_f32 v234, v234, 0
	v_lshlrev_b32_e32 v235, 16, v234
	v_add_f32_e32 v205, v211, v235
	v_exp_f32_e32 v205, v205
	v_xor_b32_e32 v211, 0x80000000, v235
	v_mov_b32_e32 v238, 0
	s_mov_b32 exec_hi, 0
	v_mov_b32_e32 v238, v234
	s_mov_b32 exec_hi, -1
	v_mov_b32_e32 v239, 0
	v_mov_b32_e32 v240, 0
	v_mov_b32_e32 v241, 0
	v_mul_f32_e32 v212, v212, v205
	v_mul_f32_e32 v32, v32, v205
	v_mul_f32_e32 v33, v33, v205
	v_mul_f32_e32 v34, v34, v205
	v_mul_f32_e32 v35, v35, v205
	v_mul_f32_e32 v36, v36, v205
	v_mul_f32_e32 v37, v37, v205
	v_mul_f32_e32 v38, v38, v205
	v_mul_f32_e32 v39, v39, v205
	v_mul_f32_e32 v40, v40, v205
	v_mul_f32_e32 v41, v41, v205
	v_mul_f32_e32 v42, v42, v205
	v_mul_f32_e32 v43, v43, v205
	v_mul_f32_e32 v44, v44, v205
	v_mul_f32_e32 v45, v45, v205
	v_mul_f32_e32 v46, v46, v205
	v_mul_f32_e32 v47, v47, v205
	v_mul_f32_e32 v48, v48, v205
	v_mul_f32_e32 v49, v49, v205
	v_mul_f32_e32 v50, v50, v205
	v_mul_f32_e32 v51, v51, v205
	v_mul_f32_e32 v52, v52, v205
	v_mul_f32_e32 v53, v53, v205
	v_mul_f32_e32 v54, v54, v205
	v_mul_f32_e32 v55, v55, v205
	v_mul_f32_e32 v56, v56, v205
	v_mul_f32_e32 v57, v57, v205
	v_mul_f32_e32 v58, v58, v205
	v_mul_f32_e32 v59, v59, v205
	v_mul_f32_e32 v60, v60, v205
	v_mul_f32_e32 v61, v61, v205
	v_mul_f32_e32 v62, v62, v205
	v_mul_f32_e32 v63, v63, v205
	v_xor_b32_e32 v234, 0x80000000, v223
	v_cvt_pk_bf16_f32 v234, v234, 0
	v_lshlrev_b32_e32 v235, 16, v234
	v_add_f32_e32 v205, v223, v235
	v_exp_f32_e32 v205, v205
	v_xor_b32_e32 v223, 0x80000000, v235
	v_mov_b32_e32 v246, 0
	s_mov_b32 exec_hi, 0
	v_mov_b32_e32 v246, v234
	s_mov_b32 exec_hi, -1
	v_mov_b32_e32 v247, 0
	v_mov_b32_e32 v248, 0
	v_mov_b32_e32 v249, 0
	v_mul_f32_e32 v213, v213, v205
	v_mul_f32_e32 v0, v0, v205
	v_mul_f32_e32 v1, v1, v205
	v_mul_f32_e32 v2, v2, v205
	v_mul_f32_e32 v3, v3, v205
	v_mul_f32_e32 v4, v4, v205
	v_mul_f32_e32 v5, v5, v205
	v_mul_f32_e32 v6, v6, v205
	v_mul_f32_e32 v7, v7, v205
	v_mul_f32_e32 v8, v8, v205
	v_mul_f32_e32 v9, v9, v205
	v_mul_f32_e32 v10, v10, v205
	v_mul_f32_e32 v11, v11, v205
	v_mul_f32_e32 v12, v12, v205
	v_mul_f32_e32 v13, v13, v205
	v_mul_f32_e32 v14, v14, v205
	v_mul_f32_e32 v15, v15, v205
	v_mul_f32_e32 v16, v16, v205
	v_mul_f32_e32 v17, v17, v205
	v_mul_f32_e32 v18, v18, v205
	v_mul_f32_e32 v19, v19, v205
	v_mul_f32_e32 v20, v20, v205
	v_mul_f32_e32 v21, v21, v205
	v_mul_f32_e32 v22, v22, v205
	v_mul_f32_e32 v23, v23, v205
	v_mul_f32_e32 v24, v24, v205
	v_mul_f32_e32 v25, v25, v205
	v_mul_f32_e32 v26, v26, v205
	v_mul_f32_e32 v27, v27, v205
	v_mul_f32_e32 v28, v28, v205
	v_mul_f32_e32 v29, v29, v205
	v_mul_f32_e32 v30, v30, v205
	v_mul_f32_e32 v31, v31, v205
	v_add_u32_e32 v250, v210, v226
	s_branch .LBB0_1484
.LBB0_1484:
	s_movk_i32 s11, 0x3400
	s_movk_i32 s19, 0x3400
	s_movk_i32 s10, 0x2400
	s_mov_b32 s21, 1
	s_waitcnt vmcnt(1)
	ds_write_b128 v224, v[152:155] offset:13312
	s_waitcnt vmcnt(0)
	ds_write_b128 v225, v[148:151] offset:35840
	s_and_saveexec_b64 s[8:9], s[6:7]
	s_cbranch_execz .LBB0_1473
	ds_write_b128 v250, v[144:147] offset:13440
	s_branch .LBB0_1473
